# strategy 1 counted waits: out-proj comp first MFMA group waits per fragment (lgkmcnt 6/9/8/7) instead of for all five first reads
# speedup vs baseline: 1.0052x; 1.0016x over previous
.LBB0_80:
	ds_read_b128 v[114:117], v127 offset:16384
	ds_read_b128 v[118:121], v0
	ds_read_b128 v[166:169], v127 offset:18432
	ds_read_b128 v[170:173], v127 offset:20480
	ds_read_b128 v[174:177], v127 offset:22528
	ds_read_b128 v[238:241], v0 offset:2048
	ds_read_b128 v[242:245], v0 offset:4096
	ds_read_b128 v[246:249], v0 offset:6144
	s_andn2_b64 vcc, exec, s[38:39]
	s_waitcnt lgkmcnt(6)
	v_mfma_f32_16x16x32_bf16 v[78:81], v[114:117], v[118:121], v[78:81]
	ds_read_b128 v[230:233], v129 offset:16384
	ds_read_b128 v[234:237], v129 offset:22528
	ds_read_b128 v[90:93], v129 offset:18432
	ds_read_b128 v[94:97], v129 offset:20480
	s_waitcnt lgkmcnt(9)
	v_mfma_f32_16x16x32_bf16 v[74:77], v[166:169], v[118:121], v[74:77]
	s_waitcnt lgkmcnt(8)
	v_mfma_f32_16x16x32_bf16 v[70:73], v[170:173], v[118:121], v[70:73]
	s_waitcnt lgkmcnt(7)
	v_mfma_f32_16x16x32_bf16 v[66:69], v[174:177], v[118:121], v[66:69]
	s_waitcnt lgkmcnt(6)
	v_mfma_f32_16x16x32_bf16 v[62:65], v[114:117], v[238:241], v[62:65]
	v_mfma_f32_16x16x32_bf16 v[58:61], v[166:169], v[238:241], v[58:61]
	v_mfma_f32_16x16x32_bf16 v[54:57], v[170:173], v[238:241], v[54:57]
	v_mfma_f32_16x16x32_bf16 v[50:53], v[174:177], v[238:241], v[50:53]
	ds_read_b128 v[238:241], v128 offset:2048
	s_waitcnt lgkmcnt(6)
	v_mfma_f32_16x16x32_bf16 v[218:221], v[114:117], v[242:245], v[46:49]
	v_mfma_f32_16x16x32_bf16 v[222:225], v[166:169], v[242:245], v[42:45]
	v_mfma_f32_16x16x32_bf16 v[226:229], v[170:173], v[242:245], v[38:41]
	v_mfma_f32_16x16x32_bf16 v[118:121], v[174:177], v[242:245], v[34:37]
	s_nop 2
	ds_read_b128 v[34:37], v128
	ds_read_b128 v[242:245], v128 offset:4096
	s_waitcnt lgkmcnt(7)
	v_mfma_f32_16x16x32_bf16 v[114:117], v[114:117], v[246:249], v[30:33]
	v_mfma_f32_16x16x32_bf16 v[166:169], v[166:169], v[246:249], v[26:29]
	v_mfma_f32_16x16x32_bf16 v[170:173], v[170:173], v[246:249], v[22:25]
	v_mfma_f32_16x16x32_bf16 v[18:21], v[174:177], v[246:249], v[18:21]
	ds_read_b128 v[246:249], v128 offset:6144
	s_waitcnt lgkmcnt(2)
	v_mfma_f32_16x16x32_bf16 v[22:25], v[230:233], v[34:37], v[78:81]
	v_mfma_f32_16x16x32_bf16 v[26:29], v[90:93], v[34:37], v[74:77]
	v_mfma_f32_16x16x32_bf16 v[30:33], v[94:97], v[34:37], v[70:73]
	v_mfma_f32_16x16x32_bf16 v[34:37], v[234:237], v[34:37], v[66:69]
	v_mfma_f32_16x16x32_bf16 v[38:41], v[230:233], v[238:241], v[62:65]
	v_mfma_f32_16x16x32_bf16 v[42:45], v[90:93], v[238:241], v[58:61]
	v_mfma_f32_16x16x32_bf16 v[46:49], v[94:97], v[238:241], v[54:57]
	v_mfma_f32_16x16x32_bf16 v[50:53], v[234:237], v[238:241], v[50:53]
	s_waitcnt lgkmcnt(1)
	v_mfma_f32_16x16x32_bf16 v[54:57], v[230:233], v[242:245], v[218:221]
	v_mfma_f32_16x16x32_bf16 v[58:61], v[90:93], v[242:245], v[222:225]
	v_mfma_f32_16x16x32_bf16 v[62:65], v[94:97], v[242:245], v[226:229]
	v_mfma_f32_16x16x32_bf16 v[66:69], v[234:237], v[242:245], v[118:121]
	s_waitcnt lgkmcnt(0)
	v_mfma_f32_16x16x32_bf16 v[70:73], v[230:233], v[246:249], v[114:117]
	v_mfma_f32_16x16x32_bf16 v[74:77], v[90:93], v[246:249], v[166:169]
	v_mfma_f32_16x16x32_bf16 v[78:81], v[94:97], v[246:249], v[170:173]
	v_mfma_f32_16x16x32_bf16 v[18:21], v[234:237], v[246:249], v[18:21]
	s_cbranch_vccnz .LBB0_82
	s_waitcnt vmcnt(0)
	ds_write_b16 v130, v2 offset:36864
	ds_write_b16_d16_hi v130, v2 offset:36992
	ds_write_b16 v131, v3 offset:36864
	ds_write_b16_d16_hi v132, v3 offset:36864
	ds_write_b16 v133, v4 offset:36864
	ds_write_b16_d16_hi v134, v4 offset:36864
	ds_write_b16 v135, v5 offset:36864
	ds_write_b16_d16_hi v136, v5 offset:36864
	ds_write_b16 v137, v6 offset:36864
	ds_write_b16_d16_hi v137, v6 offset:36992
	ds_write_b16 v138, v7 offset:36864
	ds_write_b16_d16_hi v139, v7 offset:36864
	ds_write_b16 v140, v8 offset:36864
	ds_write_b16_d16_hi v141, v8 offset:36864
	ds_write_b16 v142, v9 offset:36864
	ds_write_b16_d16_hi v143, v9 offset:36864
	ds_write_b16 v144, v10 offset:36864
	ds_write_b16_d16_hi v144, v10 offset:36992
	ds_write_b16 v145, v11 offset:36864
	ds_write_b16_d16_hi v154, v11 offset:36864
	ds_write_b16 v155, v12 offset:36864
	ds_write_b16_d16_hi v156, v12 offset:36864
	ds_write_b16 v157, v13 offset:36864
	ds_write_b16_d16_hi v158, v13 offset:36864
	ds_write_b16 v159, v14 offset:36864
	ds_write_b16_d16_hi v159, v14 offset:36992
	ds_write_b16 v160, v15 offset:36864
	ds_write_b16_d16_hi v161, v15 offset:36864
	ds_write_b16 v162, v16 offset:36864
	ds_write_b16_d16_hi v163, v16 offset:36864
	ds_write_b16 v164, v17 offset:36864
	ds_write_b16_d16_hi v165, v17 offset:36864

.LBB0_87:
	ds_read_b128 v[106:109], v127 offset:53248
	ds_read_b128 v[110:113], v0 offset:36864
	ds_read_b128 v[114:117], v127 offset:55296
	ds_read_b128 v[118:121], v127 offset:57344
	ds_read_b128 v[166:169], v127 offset:59392
	ds_read_b128 v[238:241], v0 offset:38912
	ds_read_b128 v[242:245], v0 offset:40960
	ds_read_b128 v[246:249], v0 offset:43008
	s_andn2_b64 vcc, exec, s[40:41]
	s_waitcnt lgkmcnt(6)
	v_mfma_f32_16x16x32_bf16 v[22:25], v[106:109], v[110:113], v[22:25]
	ds_read_b128 v[222:225], v129 offset:53248
	ds_read_b128 v[226:229], v129 offset:59392
	ds_read_b128 v[90:93], v129 offset:55296
	ds_read_b128 v[94:97], v129 offset:57344
	s_waitcnt lgkmcnt(9)
	v_mfma_f32_16x16x32_bf16 v[26:29], v[114:117], v[110:113], v[26:29]
	s_waitcnt lgkmcnt(8)
	v_mfma_f32_16x16x32_bf16 v[30:33], v[118:121], v[110:113], v[30:33]
	s_waitcnt lgkmcnt(7)
	v_mfma_f32_16x16x32_bf16 v[34:37], v[166:169], v[110:113], v[34:37]
	s_waitcnt lgkmcnt(6)
	v_mfma_f32_16x16x32_bf16 v[38:41], v[106:109], v[238:241], v[38:41]
	v_mfma_f32_16x16x32_bf16 v[42:45], v[114:117], v[238:241], v[42:45]
	v_mfma_f32_16x16x32_bf16 v[46:49], v[118:121], v[238:241], v[46:49]
	v_mfma_f32_16x16x32_bf16 v[50:53], v[166:169], v[238:241], v[50:53]
	ds_read_b128 v[238:241], v128 offset:38912
	s_waitcnt lgkmcnt(6)
	v_mfma_f32_16x16x32_bf16 v[170:173], v[106:109], v[242:245], v[54:57]
	v_mfma_f32_16x16x32_bf16 v[174:177], v[114:117], v[242:245], v[58:61]
	v_mfma_f32_16x16x32_bf16 v[218:221], v[118:121], v[242:245], v[62:65]
	v_mfma_f32_16x16x32_bf16 v[110:113], v[166:169], v[242:245], v[66:69]
	s_nop 2
	ds_read_b128 v[54:57], v128 offset:36864
	ds_read_b128 v[242:245], v128 offset:40960
	s_waitcnt lgkmcnt(7)
	v_mfma_f32_16x16x32_bf16 v[106:109], v[106:109], v[246:249], v[70:73]
	v_mfma_f32_16x16x32_bf16 v[114:117], v[114:117], v[246:249], v[74:77]
	v_mfma_f32_16x16x32_bf16 v[118:121], v[118:121], v[246:249], v[78:81]
	v_mfma_f32_16x16x32_bf16 v[18:21], v[166:169], v[246:249], v[18:21]
	ds_read_b128 v[246:249], v128 offset:43008
	s_waitcnt lgkmcnt(2)
	v_mfma_f32_16x16x32_bf16 v[78:81], v[222:225], v[54:57], v[22:25]
	v_mfma_f32_16x16x32_bf16 v[74:77], v[90:93], v[54:57], v[26:29]
	v_mfma_f32_16x16x32_bf16 v[70:73], v[94:97], v[54:57], v[30:33]
	v_mfma_f32_16x16x32_bf16 v[66:69], v[226:229], v[54:57], v[34:37]
	v_mfma_f32_16x16x32_bf16 v[62:65], v[222:225], v[238:241], v[38:41]
	v_mfma_f32_16x16x32_bf16 v[58:61], v[90:93], v[238:241], v[42:45]
	v_mfma_f32_16x16x32_bf16 v[54:57], v[94:97], v[238:241], v[46:49]
	v_mfma_f32_16x16x32_bf16 v[50:53], v[226:229], v[238:241], v[50:53]
	s_waitcnt lgkmcnt(1)
	v_mfma_f32_16x16x32_bf16 v[34:37], v[226:229], v[242:245], v[110:113]
	v_mfma_f32_16x16x32_bf16 v[46:49], v[222:225], v[242:245], v[170:173]
	v_mfma_f32_16x16x32_bf16 v[42:45], v[90:93], v[242:245], v[174:177]
	v_mfma_f32_16x16x32_bf16 v[38:41], v[94:97], v[242:245], v[218:221]
	s_waitcnt lgkmcnt(0)
	v_mfma_f32_16x16x32_bf16 v[30:33], v[222:225], v[246:249], v[106:109]
	v_mfma_f32_16x16x32_bf16 v[26:29], v[90:93], v[246:249], v[114:117]
	v_mfma_f32_16x16x32_bf16 v[22:25], v[94:97], v[246:249], v[118:121]
	v_mfma_f32_16x16x32_bf16 v[18:21], v[226:229], v[246:249], v[18:21]
	s_cbranch_vccnz .LBB0_75
	s_waitcnt vmcnt(0)
	ds_write_b16 v130, v2
	ds_write_b16_d16_hi v130, v2 offset:128
	ds_write_b16 v131, v3
	ds_write_b16_d16_hi v132, v3
	ds_write_b16 v133, v4
	ds_write_b16_d16_hi v134, v4
	ds_write_b16 v135, v5
	ds_write_b16_d16_hi v136, v5
	ds_write_b16 v137, v6
	ds_write_b16_d16_hi v137, v6 offset:128
	ds_write_b16 v138, v7
	ds_write_b16_d16_hi v139, v7
	ds_write_b16 v140, v8
	ds_write_b16_d16_hi v141, v8
	ds_write_b16 v142, v9
	ds_write_b16_d16_hi v143, v9
	ds_write_b16 v144, v10
	ds_write_b16_d16_hi v144, v10 offset:128
	ds_write_b16 v145, v11
	ds_write_b16_d16_hi v154, v11
	ds_write_b16 v155, v12
	ds_write_b16_d16_hi v156, v12
	ds_write_b16 v157, v13
	ds_write_b16_d16_hi v158, v13
	ds_write_b16 v159, v14
	ds_write_b16_d16_hi v159, v14 offset:128
	ds_write_b16 v160, v15
	ds_write_b16_d16_hi v161, v15
	ds_write_b16 v162, v16
	ds_write_b16_d16_hi v163, v16
	ds_write_b16 v164, v17
	ds_write_b16_d16_hi v165, v17
	s_branch .LBB0_75
